# phase0 batched loads + ckv unroll, EpiG2 cqss hoist, hand-pipelined phase1 (double-buffered x loads)
# speedup vs baseline: 1.0069x; 1.0069x over previous
; DI void phase1(const P& p) {
;   const int lane = threadIdx.x & 63, gw = blockIdx.x * 8 + (threadIdx.x >> 6), ngw = gridDim.x * 8;
;   const float* mod = (const float*)(p.ws + OFF_MOD);
;   u16* hb = (u16*)(p.ws + OFF_H);
;   const f32x4* g4 = (const f32x4*)p.pre_g;
;   for (int row = gw * 2; row < NTOK; row += ngw * 2) {
;     const float* xr; int bm;
;     if (row < NTOK_P) { xr = p.x_prompt + (size_t)row * 1024; bm = row >> 11; }
;     else { xr = p.x_sample + (size_t)(row - NTOK_P) * 1024; bm = 32 + ((row - NTOK_P) >> 6); }
;     const f32x4* x4 = (const f32x4*)xr;
;     const f32x4* sh4 = (const f32x4*)(mod + bm * 3072);
;     const f32x4* sc4 = (const f32x4*)(mod + bm * 3072 + 1024);
;     f32x4 v[2][4]; float ss0 = 0.f, ss1 = 0.f;
; #pragma unroll
;     for (int j = 0; j < 4; ++j) { v[0][j] = __builtin_nontemporal_load(x4 + lane + 64 * j); v[1][j] = __builtin_nontemporal_load(x4 + 256 + lane + 64 * j); }
; #pragma unroll
;     for (int j = 0; j < 4; ++j) {
;       ss0 += v[0][j].x * v[0][j].x + v[0][j].y * v[0][j].y + v[0][j].z * v[0][j].z + v[0][j].w * v[0][j].w;
;       ss1 += v[1][j].x * v[1][j].x + v[1][j].y * v[1][j].y + v[1][j].z * v[1][j].z + v[1][j].w * v[1][j].w;
;     }
; #pragma unroll
;     for (int o = 1; o < 64; o <<= 1) { ss0 += __shfl_xor(ss0, o); ss1 += __shfl_xor(ss1, o); }
;     const float r0 = rsqrtf(ss0 * (1.f / 1024.f) + EPS), r1 = rsqrtf(ss1 * (1.f / 1024.f) + EPS);
.LBB0_156:
	s_cmp_gt_i32 s30, 1
	s_cselect_b64 s[0:1], -1, 0
	s_cmp_lt_i32 s31, 2
	s_cselect_b64 s[4:5], -1, 0
	s_or_b64 s[0:1], s[0:1], s[4:5]
	s_and_b64 vcc, exec, s[0:1]
	v_lshrrev_b32_e32 v186, 5, v0
	s_cbranch_vccnz .LBB0_176
	s_mov_b64 s[4:5], exec
	s_lshl_b32 s0, s2, 4
	v_and_or_b32 v26, v186, 14, s0
	v_and_b32_e32 v1, 0x3ff, v0
	v_readfirstlane_b32 s20, v26
	s_lshl_b32 s21, s33, 4
	v_and_b32_e32 v11, 63, v0
	s_cmp_lt_u32 s20, 0x10400
	s_cbranch_scc0 .LBB0_164
	v_lshlrev_b32_e32 v2, 4, v11
	v_add_u32_e32 v3, 0x1000, v2
	v_lshlrev_b32_e32 v4, 3, v11
	v_xor_b32_e32 v5, 1, v11
	v_lshlrev_b32_e32 v5, 2, v5
	v_xor_b32_e32 v6, 2, v11
	v_lshlrev_b32_e32 v6, 2, v6
	v_xor_b32_e32 v7, 4, v11
	v_lshlrev_b32_e32 v7, 2, v7
	v_xor_b32_e32 v8, 8, v11
	v_lshlrev_b32_e32 v8, 2, v8
	v_xor_b32_e32 v9, 16, v11
	v_lshlrev_b32_e32 v9, 2, v9
	v_xor_b32_e32 v10, 32, v11
	v_lshlrev_b32_e32 v10, 2, v10
	global_load_dwordx4 v[12:15], v2, s[40:41] offset:0
	global_load_dwordx4 v[16:19], v2, s[40:41] offset:1024
	global_load_dwordx4 v[20:23], v2, s[40:41] offset:2048
	global_load_dwordx4 v[24:27], v2, s[40:41] offset:3072
	s_cmp_lt_u32 s20, 0x10000
	s_cbranch_scc0 .Lp1_sx1
	s_lshl_b32 s0, s20, 12
	s_add_u32 s34, s12, s0
	s_addc_u32 s35, s13, 0
	s_branch .Lp1_xd1
.Lp1_sx1:
	s_sub_u32 s0, s20, 0x10000
	s_lshl_b32 s0, s0, 12
	s_add_u32 s34, s14, s0
	s_addc_u32 s35, s15, 0
.Lp1_xd1:
	global_load_dwordx4 v[28:31], v2, s[34:35] offset:0 nt
	global_load_dwordx4 v[32:35], v2, s[34:35] offset:1024 nt
	global_load_dwordx4 v[36:39], v2, s[34:35] offset:2048 nt
	global_load_dwordx4 v[40:43], v2, s[34:35] offset:3072 nt
	global_load_dwordx4 v[44:47], v3, s[34:35] offset:0 nt
	global_load_dwordx4 v[48:51], v3, s[34:35] offset:1024 nt
	global_load_dwordx4 v[52:55], v3, s[34:35] offset:2048 nt
	global_load_dwordx4 v[56:59], v3, s[34:35] offset:3072 nt
.Lp1_loopA:
	s_add_u32 s36, s20, s21
	s_cmp_lt_u32 s20, 0x10000
	s_cbranch_scc0 .Lp1_sm2
	s_lshr_b32 s0, s20, 11
	s_branch .Lp1_md2
.Lp1_sm2:
	s_sub_u32 s0, s20, 0x10000
	s_lshr_b32 s0, s0, 6
	s_add_u32 s0, s0, 32
.Lp1_md2:
	s_mul_i32 s0, s0, 0x3000
	s_add_u32 s0, s0, 0x100
	s_add_u32 s24, s58, s0
	s_addc_u32 s25, s59, 0
	s_lshl_b32 s0, s20, 11
	s_add_u32 s0, s0, 0xbe8100
	s_add_u32 s26, s58, s0
	s_addc_u32 s27, s59, 0
	global_load_dwordx4 v[96:99], v3, s[24:25] offset:0
	global_load_dwordx4 v[100:103], v3, s[24:25] offset:1024
	global_load_dwordx4 v[104:107], v3, s[24:25] offset:2048
	global_load_dwordx4 v[108:111], v3, s[24:25] offset:3072
	global_load_dwordx4 v[232:235], v2, s[24:25] offset:0
	global_load_dwordx4 v[236:239], v2, s[24:25] offset:1024
	global_load_dwordx4 v[240:243], v2, s[24:25] offset:2048
	global_load_dwordx4 v[244:247], v2, s[24:25] offset:3072
	s_cmp_lt_u32 s36, 0x10400
	s_cbranch_scc0 .Lp1_nonextA
	s_cmp_lt_u32 s36, 0x10000
	s_cbranch_scc0 .Lp1_sx3
	s_lshl_b32 s0, s36, 12
	s_add_u32 s34, s12, s0
	s_addc_u32 s35, s13, 0
	s_branch .Lp1_xd3
.Lp1_sx3:
	s_sub_u32 s0, s36, 0x10000
	s_lshl_b32 s0, s0, 12
	s_add_u32 s34, s14, s0
	s_addc_u32 s35, s15, 0
.Lp1_xd3:
	global_load_dwordx4 v[64:67], v2, s[34:35] offset:0 nt
	global_load_dwordx4 v[68:71], v2, s[34:35] offset:1024 nt
	global_load_dwordx4 v[72:75], v2, s[34:35] offset:2048 nt
	global_load_dwordx4 v[76:79], v2, s[34:35] offset:3072 nt
	global_load_dwordx4 v[80:83], v3, s[34:35] offset:0 nt
	global_load_dwordx4 v[84:87], v3, s[34:35] offset:1024 nt
	global_load_dwordx4 v[88:91], v3, s[34:35] offset:2048 nt
	global_load_dwordx4 v[92:95], v3, s[34:35] offset:3072 nt
	s_waitcnt vmcnt(16)
	s_branch .Lp1_goA
.Lp1_nonextA:
	s_waitcnt vmcnt(8)
.Lp1_goA:
	v_mul_f32_e32 v60, v28, v28
	v_fmac_f32_e32 v60, v29, v29
	v_fmac_f32_e32 v60, v30, v30
	v_fmac_f32_e32 v60, v31, v31
	v_fmac_f32_e32 v60, v32, v32
	v_fmac_f32_e32 v60, v33, v33
	v_fmac_f32_e32 v60, v34, v34
	v_fmac_f32_e32 v60, v35, v35
	v_fmac_f32_e32 v60, v36, v36
	v_fmac_f32_e32 v60, v37, v37
	v_fmac_f32_e32 v60, v38, v38
	v_fmac_f32_e32 v60, v39, v39
	v_fmac_f32_e32 v60, v40, v40
	v_fmac_f32_e32 v60, v41, v41
	v_fmac_f32_e32 v60, v42, v42
	v_fmac_f32_e32 v60, v43, v43
	v_mul_f32_e32 v61, v44, v44
	v_fmac_f32_e32 v61, v45, v45
	v_fmac_f32_e32 v61, v46, v46
	v_fmac_f32_e32 v61, v47, v47
	v_fmac_f32_e32 v61, v48, v48
	v_fmac_f32_e32 v61, v49, v49
	v_fmac_f32_e32 v61, v50, v50
	v_fmac_f32_e32 v61, v51, v51
	v_fmac_f32_e32 v61, v52, v52
	v_fmac_f32_e32 v61, v53, v53
	v_fmac_f32_e32 v61, v54, v54
	v_fmac_f32_e32 v61, v55, v55
	v_fmac_f32_e32 v61, v56, v56
	v_fmac_f32_e32 v61, v57, v57
	v_fmac_f32_e32 v61, v58, v58
	v_fmac_f32_e32 v61, v59, v59
	ds_bpermute_b32 v62, v5, v60
	ds_bpermute_b32 v11, v5, v61
	s_waitcnt lgkmcnt(0)
	v_add_f32_e32 v60, v60, v62
	v_add_f32_e32 v61, v61, v11
	ds_bpermute_b32 v62, v6, v60
	ds_bpermute_b32 v11, v6, v61
	s_waitcnt lgkmcnt(0)
	v_add_f32_e32 v60, v60, v62
	v_add_f32_e32 v61, v61, v11
	ds_bpermute_b32 v62, v7, v60
	ds_bpermute_b32 v11, v7, v61
	s_waitcnt lgkmcnt(0)
	v_add_f32_e32 v60, v60, v62
	v_add_f32_e32 v61, v61, v11
	ds_bpermute_b32 v62, v8, v60
	ds_bpermute_b32 v11, v8, v61
	s_waitcnt lgkmcnt(0)
	v_add_f32_e32 v60, v60, v62
	v_add_f32_e32 v61, v61, v11
	ds_bpermute_b32 v62, v9, v60
	ds_bpermute_b32 v11, v9, v61
	s_waitcnt lgkmcnt(0)
	v_add_f32_e32 v60, v60, v62
	v_add_f32_e32 v61, v61, v11
	ds_bpermute_b32 v62, v10, v60
	ds_bpermute_b32 v11, v10, v61
	s_waitcnt lgkmcnt(0)
	v_add_f32_e32 v60, v60, v62
	v_add_f32_e32 v61, v61, v11
	v_mov_b32_e32 v62, 0x358637bd
	v_fmac_f32_e32 v62, 0x3a800000, v60
	v_mov_b32_e32 v11, 0x358637bd
	v_fmac_f32_e32 v11, 0x3a800000, v61
	v_mul_f32_e32 v60, 0x4b800000, v62
	v_cmp_gt_f32_e32 vcc, 0x800000, v62
	v_mul_f32_e32 v61, 0x4b800000, v11
	v_mov_b32_e32 v112, 0x800000
	v_cmp_lt_f32_e64 s[0:1], v11, v112
	v_cndmask_b32_e32 v60, v62, v60, vcc
	v_rsq_f32_e32 v60, v60
	s_nop 0
	v_cndmask_b32_e64 v61, v11, v61, s[0:1]
	v_rsq_f32_e32 v61, v61
	v_mul_f32_e32 v62, 0x45800000, v60
	v_cndmask_b32_e32 v60, v60, v62, vcc
	v_mul_f32_e32 v11, 0x45800000, v61
	v_cndmask_b32_e64 v61, v61, v11, s[0:1]
	s_cmp_lt_u32 s36, 0x10400
	s_cbranch_scc0 .Lp1_w0A
	s_waitcnt vmcnt(8)
	s_branch .Lp1_w1A

; DI void phase1(const P& p) {
;     ...
; #pragma unroll
;     for (int j = 0; j < 4; ++j) {
;       const int c4 = lane + 64 * j;
;       const f32x4 g = g4[c4], sc = sc4[c4], sh = sh4[c4];
;       const f32x4 m = g * (sc + 1.f);
;       const f32x4 a = v[0][j] * r0 * m + sh, bq = v[1][j] * r1 * m + sh;
;       *(u32x2*)(hb + (size_t)row * 1024 + c4 * 4) = (u32x2){pk2(a.x, a.y), pk2(a.z, a.w)};
;       *(u32x2*)(hb + (size_t)(row + 1) * 1024 + c4 * 4) = (u32x2){pk2(bq.x, bq.y), pk2(bq.z, bq.w)};
;     }
;   }
.Lp1_w1A:
	v_add_f32_e32 v96, 1.0, v96
	v_mul_f32_e32 v96, v12, v96
	v_add_f32_e32 v97, 1.0, v97
	v_mul_f32_e32 v97, v13, v97
	v_add_f32_e32 v98, 1.0, v98
	v_mul_f32_e32 v98, v14, v98
	v_add_f32_e32 v99, 1.0, v99
	v_mul_f32_e32 v99, v15, v99
	v_mul_f32_e32 v28, v28, v60
	v_mul_f32_e32 v29, v29, v60
	v_mul_f32_e32 v30, v30, v60
	v_mul_f32_e32 v31, v31, v60
	v_fma_f32 v28, v96, v28, v232
	v_fma_f32 v29, v97, v29, v233
	v_fma_f32 v30, v98, v30, v234
	v_fma_f32 v31, v99, v31, v235
	v_cvt_pk_bf16_f32 v28, v28, v29
	v_cvt_pk_bf16_f32 v29, v30, v31
	global_store_dwordx2 v4, v[28:29], s[26:27] offset:0
	v_mul_f32_e32 v44, v44, v61
	v_mul_f32_e32 v45, v45, v61
	v_mul_f32_e32 v46, v46, v61
	v_mul_f32_e32 v47, v47, v61
	v_fma_f32 v44, v96, v44, v232
	v_fma_f32 v45, v97, v45, v233
	v_fma_f32 v46, v98, v46, v234
	v_fma_f32 v47, v99, v47, v235
	v_cvt_pk_bf16_f32 v44, v44, v45
	v_cvt_pk_bf16_f32 v45, v46, v47
	global_store_dwordx2 v4, v[44:45], s[26:27] offset:2048
	v_add_f32_e32 v100, 1.0, v100
	v_mul_f32_e32 v100, v16, v100
	v_add_f32_e32 v101, 1.0, v101
	v_mul_f32_e32 v101, v17, v101
	v_add_f32_e32 v102, 1.0, v102
	v_mul_f32_e32 v102, v18, v102
	v_add_f32_e32 v103, 1.0, v103
	v_mul_f32_e32 v103, v19, v103
	v_mul_f32_e32 v32, v32, v60
	v_mul_f32_e32 v33, v33, v60
	v_mul_f32_e32 v34, v34, v60
	v_mul_f32_e32 v35, v35, v60
	v_fma_f32 v32, v100, v32, v236
	v_fma_f32 v33, v101, v33, v237
	v_fma_f32 v34, v102, v34, v238
	v_fma_f32 v35, v103, v35, v239
	v_cvt_pk_bf16_f32 v32, v32, v33
	v_cvt_pk_bf16_f32 v33, v34, v35
	global_store_dwordx2 v4, v[32:33], s[26:27] offset:512
	v_mul_f32_e32 v48, v48, v61
	v_mul_f32_e32 v49, v49, v61
	v_mul_f32_e32 v50, v50, v61
	v_mul_f32_e32 v51, v51, v61
	v_fma_f32 v48, v100, v48, v236
	v_fma_f32 v49, v101, v49, v237
	v_fma_f32 v50, v102, v50, v238
	v_fma_f32 v51, v103, v51, v239
	v_cvt_pk_bf16_f32 v48, v48, v49
	v_cvt_pk_bf16_f32 v49, v50, v51
	global_store_dwordx2 v4, v[48:49], s[26:27] offset:2560
	v_add_f32_e32 v104, 1.0, v104
	v_mul_f32_e32 v104, v20, v104
	v_add_f32_e32 v105, 1.0, v105
	v_mul_f32_e32 v105, v21, v105
	v_add_f32_e32 v106, 1.0, v106
	v_mul_f32_e32 v106, v22, v106
	v_add_f32_e32 v107, 1.0, v107
	v_mul_f32_e32 v107, v23, v107
	v_mul_f32_e32 v36, v36, v60
	v_mul_f32_e32 v37, v37, v60
	v_mul_f32_e32 v38, v38, v60
	v_mul_f32_e32 v39, v39, v60
	v_fma_f32 v36, v104, v36, v240
	v_fma_f32 v37, v105, v37, v241
	v_fma_f32 v38, v106, v38, v242
	v_fma_f32 v39, v107, v39, v243
	v_cvt_pk_bf16_f32 v36, v36, v37
	v_cvt_pk_bf16_f32 v37, v38, v39
	global_store_dwordx2 v4, v[36:37], s[26:27] offset:1024
	v_mul_f32_e32 v52, v52, v61
	v_mul_f32_e32 v53, v53, v61
	v_mul_f32_e32 v54, v54, v61
	v_mul_f32_e32 v55, v55, v61
	v_fma_f32 v52, v104, v52, v240
	v_fma_f32 v53, v105, v53, v241
	v_fma_f32 v54, v106, v54, v242
	v_fma_f32 v55, v107, v55, v243
	v_cvt_pk_bf16_f32 v52, v52, v53
	v_cvt_pk_bf16_f32 v53, v54, v55
	global_store_dwordx2 v4, v[52:53], s[26:27] offset:3072
	v_add_f32_e32 v108, 1.0, v108
	v_mul_f32_e32 v108, v24, v108
	v_add_f32_e32 v109, 1.0, v109
	v_mul_f32_e32 v109, v25, v109
	v_add_f32_e32 v110, 1.0, v110
	v_mul_f32_e32 v110, v26, v110
	v_add_f32_e32 v111, 1.0, v111
	v_mul_f32_e32 v111, v27, v111
	v_mul_f32_e32 v40, v40, v60
	v_mul_f32_e32 v41, v41, v60
	v_mul_f32_e32 v42, v42, v60
	v_mul_f32_e32 v43, v43, v60
	v_fma_f32 v40, v108, v40, v244
	v_fma_f32 v41, v109, v41, v245
	v_fma_f32 v42, v110, v42, v246
	v_fma_f32 v43, v111, v43, v247
	v_cvt_pk_bf16_f32 v40, v40, v41
	v_cvt_pk_bf16_f32 v41, v42, v43
	global_store_dwordx2 v4, v[40:41], s[26:27] offset:1536
	v_mul_f32_e32 v56, v56, v61
	v_mul_f32_e32 v57, v57, v61
	v_mul_f32_e32 v58, v58, v61
	v_mul_f32_e32 v59, v59, v61
	v_fma_f32 v56, v108, v56, v244
	v_fma_f32 v57, v109, v57, v245
	v_fma_f32 v58, v110, v58, v246
	v_fma_f32 v59, v111, v59, v247
	v_cvt_pk_bf16_f32 v56, v56, v57
	v_cvt_pk_bf16_f32 v57, v58, v59
	global_store_dwordx2 v4, v[56:57], s[26:27] offset:3584
	s_cmp_lt_u32 s36, 0x10400
	s_cbranch_scc0 .Lp1_done
	s_mov_b32 s20, s36
	s_add_u32 s36, s20, s21
	s_cmp_lt_u32 s20, 0x10000
	s_cbranch_scc0 .Lp1_sm4
	s_lshr_b32 s0, s20, 11
	s_branch .Lp1_md4

; DI void phase1(const P& p) {
;     ...
;   for (int row = gw * 2; row < NTOK; row += ngw * 2) {
;     const float* xr; int bm;
;     if (row < NTOK_P) { xr = p.x_prompt + (size_t)row * 1024; bm = row >> 11; }
;     else { xr = p.x_sample + (size_t)(row - NTOK_P) * 1024; bm = 32 + ((row - NTOK_P) >> 6); }
;     const f32x4* x4 = (const f32x4*)xr;
;     const f32x4* sh4 = (const f32x4*)(mod + bm * 3072);
;     const f32x4* sc4 = (const f32x4*)(mod + bm * 3072 + 1024);
;     f32x4 v[2][4]; float ss0 = 0.f, ss1 = 0.f;
; #pragma unroll
;     for (int j = 0; j < 4; ++j) { v[0][j] = __builtin_nontemporal_load(x4 + lane + 64 * j); v[1][j] = __builtin_nontemporal_load(x4 + 256 + lane + 64 * j); }
.Lp1_xd5:
	global_load_dwordx4 v[28:31], v2, s[34:35] offset:0 nt
	global_load_dwordx4 v[32:35], v2, s[34:35] offset:1024 nt
	global_load_dwordx4 v[36:39], v2, s[34:35] offset:2048 nt
	global_load_dwordx4 v[40:43], v2, s[34:35] offset:3072 nt
	global_load_dwordx4 v[44:47], v3, s[34:35] offset:0 nt
	global_load_dwordx4 v[48:51], v3, s[34:35] offset:1024 nt
	global_load_dwordx4 v[52:55], v3, s[34:35] offset:2048 nt
	global_load_dwordx4 v[56:59], v3, s[34:35] offset:3072 nt
	s_waitcnt vmcnt(16)
	s_branch .Lp1_goB

; DI void phase1(const P& p) {
;     ...
;     for (int j = 0; j < 4; ++j) {
;       ss0 += v[0][j].x * v[0][j].x + v[0][j].y * v[0][j].y + v[0][j].z * v[0][j].z + v[0][j].w * v[0][j].w;
;       ss1 += v[1][j].x * v[1][j].x + v[1][j].y * v[1][j].y + v[1][j].z * v[1][j].z + v[1][j].w * v[1][j].w;
;     }
; #pragma unroll
;     for (int o = 1; o < 64; o <<= 1) { ss0 += __shfl_xor(ss0, o); ss1 += __shfl_xor(ss1, o); }
;     const float r0 = rsqrtf(ss0 * (1.f / 1024.f) + EPS), r1 = rsqrtf(ss1 * (1.f / 1024.f) + EPS);
.Lp1_goB:
	v_mul_f32_e32 v60, v64, v64
	v_fmac_f32_e32 v60, v65, v65
	v_fmac_f32_e32 v60, v66, v66
	v_fmac_f32_e32 v60, v67, v67
	v_fmac_f32_e32 v60, v68, v68
	v_fmac_f32_e32 v60, v69, v69
	v_fmac_f32_e32 v60, v70, v70
	v_fmac_f32_e32 v60, v71, v71
	v_fmac_f32_e32 v60, v72, v72
	v_fmac_f32_e32 v60, v73, v73
	v_fmac_f32_e32 v60, v74, v74
	v_fmac_f32_e32 v60, v75, v75
	v_fmac_f32_e32 v60, v76, v76
	v_fmac_f32_e32 v60, v77, v77
	v_fmac_f32_e32 v60, v78, v78
	v_fmac_f32_e32 v60, v79, v79
	v_mul_f32_e32 v61, v80, v80
	v_fmac_f32_e32 v61, v81, v81
	v_fmac_f32_e32 v61, v82, v82
	v_fmac_f32_e32 v61, v83, v83
	v_fmac_f32_e32 v61, v84, v84
	v_fmac_f32_e32 v61, v85, v85
	v_fmac_f32_e32 v61, v86, v86
	v_fmac_f32_e32 v61, v87, v87
	v_fmac_f32_e32 v61, v88, v88
	v_fmac_f32_e32 v61, v89, v89
	v_fmac_f32_e32 v61, v90, v90
	v_fmac_f32_e32 v61, v91, v91
	v_fmac_f32_e32 v61, v92, v92
	v_fmac_f32_e32 v61, v93, v93
	v_fmac_f32_e32 v61, v94, v94
	v_fmac_f32_e32 v61, v95, v95
	ds_bpermute_b32 v62, v5, v60
	ds_bpermute_b32 v11, v5, v61
	s_waitcnt lgkmcnt(0)
	v_add_f32_e32 v60, v60, v62
	v_add_f32_e32 v61, v61, v11
	ds_bpermute_b32 v62, v6, v60
	ds_bpermute_b32 v11, v6, v61
	s_waitcnt lgkmcnt(0)
	v_add_f32_e32 v60, v60, v62
	v_add_f32_e32 v61, v61, v11
	ds_bpermute_b32 v62, v7, v60
	ds_bpermute_b32 v11, v7, v61
	s_waitcnt lgkmcnt(0)
	v_add_f32_e32 v60, v60, v62
	v_add_f32_e32 v61, v61, v11
	ds_bpermute_b32 v62, v8, v60
	ds_bpermute_b32 v11, v8, v61
	s_waitcnt lgkmcnt(0)
	v_add_f32_e32 v60, v60, v62
	v_add_f32_e32 v61, v61, v11
	ds_bpermute_b32 v62, v9, v60
	ds_bpermute_b32 v11, v9, v61
	s_waitcnt lgkmcnt(0)
	v_add_f32_e32 v60, v60, v62
	v_add_f32_e32 v61, v61, v11
	ds_bpermute_b32 v62, v10, v60
	ds_bpermute_b32 v11, v10, v61
	s_waitcnt lgkmcnt(0)
	v_add_f32_e32 v60, v60, v62
	v_add_f32_e32 v61, v61, v11
	v_mov_b32_e32 v62, 0x358637bd
	v_fmac_f32_e32 v62, 0x3a800000, v60
	v_mov_b32_e32 v11, 0x358637bd
	v_fmac_f32_e32 v11, 0x3a800000, v61
	v_mul_f32_e32 v60, 0x4b800000, v62
	v_cmp_gt_f32_e32 vcc, 0x800000, v62
	v_mul_f32_e32 v61, 0x4b800000, v11
	v_mov_b32_e32 v112, 0x800000
	v_cmp_lt_f32_e64 s[0:1], v11, v112
	v_cndmask_b32_e32 v60, v62, v60, vcc
	v_rsq_f32_e32 v60, v60
	s_nop 0
	v_cndmask_b32_e64 v61, v11, v61, s[0:1]
	v_rsq_f32_e32 v61, v61
	v_mul_f32_e32 v62, 0x45800000, v60
	v_cndmask_b32_e32 v60, v60, v62, vcc
	v_mul_f32_e32 v11, 0x45800000, v61
	v_cndmask_b32_e64 v61, v61, v11, s[0:1]
	s_cmp_lt_u32 s36, 0x10400
	s_cbranch_scc0 .Lp1_w0B
	s_waitcnt vmcnt(8)
	s_branch .Lp1_w1B

; DI void phase1(const P& p) {
;     ...
; #pragma unroll
;     for (int j = 0; j < 4; ++j) {
;       const int c4 = lane + 64 * j;
;       const f32x4 g = g4[c4], sc = sc4[c4], sh = sh4[c4];
;       const f32x4 m = g * (sc + 1.f);
;       const f32x4 a = v[0][j] * r0 * m + sh, bq = v[1][j] * r1 * m + sh;
;       *(u32x2*)(hb + (size_t)row * 1024 + c4 * 4) = (u32x2){pk2(a.x, a.y), pk2(a.z, a.w)};
;       *(u32x2*)(hb + (size_t)(row + 1) * 1024 + c4 * 4) = (u32x2){pk2(bq.x, bq.y), pk2(bq.z, bq.w)};
;     }
;   }
.Lp1_w1B:
	v_add_f32_e32 v96, 1.0, v96
	v_mul_f32_e32 v96, v12, v96
	v_add_f32_e32 v97, 1.0, v97
	v_mul_f32_e32 v97, v13, v97
	v_add_f32_e32 v98, 1.0, v98
	v_mul_f32_e32 v98, v14, v98
	v_add_f32_e32 v99, 1.0, v99
	v_mul_f32_e32 v99, v15, v99
	v_mul_f32_e32 v64, v64, v60
	v_mul_f32_e32 v65, v65, v60
	v_mul_f32_e32 v66, v66, v60
	v_mul_f32_e32 v67, v67, v60
	v_fma_f32 v64, v96, v64, v232
	v_fma_f32 v65, v97, v65, v233
	v_fma_f32 v66, v98, v66, v234
	v_fma_f32 v67, v99, v67, v235
	v_cvt_pk_bf16_f32 v64, v64, v65
	v_cvt_pk_bf16_f32 v65, v66, v67
	global_store_dwordx2 v4, v[64:65], s[26:27] offset:0
	v_mul_f32_e32 v80, v80, v61
	v_mul_f32_e32 v81, v81, v61
	v_mul_f32_e32 v82, v82, v61
	v_mul_f32_e32 v83, v83, v61
	v_fma_f32 v80, v96, v80, v232
	v_fma_f32 v81, v97, v81, v233
	v_fma_f32 v82, v98, v82, v234
	v_fma_f32 v83, v99, v83, v235
	v_cvt_pk_bf16_f32 v80, v80, v81
	v_cvt_pk_bf16_f32 v81, v82, v83
	global_store_dwordx2 v4, v[80:81], s[26:27] offset:2048
	v_add_f32_e32 v100, 1.0, v100
	v_mul_f32_e32 v100, v16, v100
	v_add_f32_e32 v101, 1.0, v101
	v_mul_f32_e32 v101, v17, v101
	v_add_f32_e32 v102, 1.0, v102
	v_mul_f32_e32 v102, v18, v102
	v_add_f32_e32 v103, 1.0, v103
	v_mul_f32_e32 v103, v19, v103
	v_mul_f32_e32 v68, v68, v60
	v_mul_f32_e32 v69, v69, v60
	v_mul_f32_e32 v70, v70, v60
	v_mul_f32_e32 v71, v71, v60
	v_fma_f32 v68, v100, v68, v236
	v_fma_f32 v69, v101, v69, v237
	v_fma_f32 v70, v102, v70, v238
	v_fma_f32 v71, v103, v71, v239
	v_cvt_pk_bf16_f32 v68, v68, v69
	v_cvt_pk_bf16_f32 v69, v70, v71
	global_store_dwordx2 v4, v[68:69], s[26:27] offset:512
	v_mul_f32_e32 v84, v84, v61
	v_mul_f32_e32 v85, v85, v61
	v_mul_f32_e32 v86, v86, v61
	v_mul_f32_e32 v87, v87, v61
	v_fma_f32 v84, v100, v84, v236
	v_fma_f32 v85, v101, v85, v237
	v_fma_f32 v86, v102, v86, v238
	v_fma_f32 v87, v103, v87, v239
	v_cvt_pk_bf16_f32 v84, v84, v85
	v_cvt_pk_bf16_f32 v85, v86, v87
	global_store_dwordx2 v4, v[84:85], s[26:27] offset:2560
	v_add_f32_e32 v104, 1.0, v104
	v_mul_f32_e32 v104, v20, v104
	v_add_f32_e32 v105, 1.0, v105
	v_mul_f32_e32 v105, v21, v105
	v_add_f32_e32 v106, 1.0, v106
	v_mul_f32_e32 v106, v22, v106
	v_add_f32_e32 v107, 1.0, v107
	v_mul_f32_e32 v107, v23, v107
	v_mul_f32_e32 v72, v72, v60
	v_mul_f32_e32 v73, v73, v60
	v_mul_f32_e32 v74, v74, v60
	v_mul_f32_e32 v75, v75, v60
	v_fma_f32 v72, v104, v72, v240
	v_fma_f32 v73, v105, v73, v241
	v_fma_f32 v74, v106, v74, v242
	v_fma_f32 v75, v107, v75, v243
	v_cvt_pk_bf16_f32 v72, v72, v73
	v_cvt_pk_bf16_f32 v73, v74, v75
	global_store_dwordx2 v4, v[72:73], s[26:27] offset:1024
	v_mul_f32_e32 v88, v88, v61
	v_mul_f32_e32 v89, v89, v61
	v_mul_f32_e32 v90, v90, v61
	v_mul_f32_e32 v91, v91, v61
	v_fma_f32 v88, v104, v88, v240
	v_fma_f32 v89, v105, v89, v241
	v_fma_f32 v90, v106, v90, v242
	v_fma_f32 v91, v107, v91, v243
	v_cvt_pk_bf16_f32 v88, v88, v89
	v_cvt_pk_bf16_f32 v89, v90, v91
	global_store_dwordx2 v4, v[88:89], s[26:27] offset:3072
	v_add_f32_e32 v108, 1.0, v108
	v_mul_f32_e32 v108, v24, v108
	v_add_f32_e32 v109, 1.0, v109
	v_mul_f32_e32 v109, v25, v109
	v_add_f32_e32 v110, 1.0, v110
	v_mul_f32_e32 v110, v26, v110
	v_add_f32_e32 v111, 1.0, v111
	v_mul_f32_e32 v111, v27, v111
	v_mul_f32_e32 v76, v76, v60
	v_mul_f32_e32 v77, v77, v60
	v_mul_f32_e32 v78, v78, v60
	v_mul_f32_e32 v79, v79, v60
	v_fma_f32 v76, v108, v76, v244
	v_fma_f32 v77, v109, v77, v245
	v_fma_f32 v78, v110, v78, v246
	v_fma_f32 v79, v111, v79, v247
	v_cvt_pk_bf16_f32 v76, v76, v77
	v_cvt_pk_bf16_f32 v77, v78, v79
	global_store_dwordx2 v4, v[76:77], s[26:27] offset:1536
	v_mul_f32_e32 v92, v92, v61
	v_mul_f32_e32 v93, v93, v61
	v_mul_f32_e32 v94, v94, v61
	v_mul_f32_e32 v95, v95, v61
	v_fma_f32 v92, v108, v92, v244
	v_fma_f32 v93, v109, v93, v245
	v_fma_f32 v94, v110, v94, v246
	v_fma_f32 v95, v111, v95, v247
	v_cvt_pk_bf16_f32 v92, v92, v93
	v_cvt_pk_bf16_f32 v93, v94, v95
	global_store_dwordx2 v4, v[92:93], s[26:27] offset:3584
	s_cmp_lt_u32 s36, 0x10400
	s_cbranch_scc0 .Lp1_done
	s_mov_b32 s20, s36
	s_branch .Lp1_loopA
.Lp1_done:
	s_waitcnt vmcnt(0)
.LBB0_164:
	s_or_b64 exec, exec, s[4:5]
	s_cmp_lt_i32 s31, 3
	s_cbranch_scc1 .LBB0_176
	v_lshrrev_b32_e32 v2, 20, v0
	v_lshrrev_b32_e32 v3, 10, v0
	v_or_b32_e32 v2, v3, v2
	s_movk_i32 s0, 0x3ff
	v_and_or_b32 v1, v2, s0, v1
	v_cmp_eq_u32_e32 vcc, 0, v1
	s_barrier
	s_and_saveexec_b64 s[0:1], vcc
	s_cbranch_execz .LBB0_175
	buffer_wbl2 sc1
	s_waitcnt vmcnt(0)
	s_load_dwordx2 s[4:5], s[28:29], 0x58
	v_mov_b32_e32 v3, 0
	s_mov_b64 s[6:7], exec
	v_mbcnt_lo_u32_b32 v2, s6, 0
	v_mbcnt_hi_u32_b32 v2, s7, v2
	s_waitcnt lgkmcnt(0)
	global_load_dword v1, v3, s[4:5] offset:40
	v_cmp_eq_u32_e32 vcc, 0, v2
	s_and_saveexec_b64 s[8:9], vcc
	s_cbranch_execz .LBB0_168
	s_bcnt1_i32_b64 s3, s[6:7]
	v_mov_b32_e32 v4, s3
	global_atomic_add v4, v3, v4, s[4:5] offset:32 sc0
